# grid barrier: non-leader workgroups poll the cross-XCD release word directly instead of the per-XCD relay word (one fewer detection hop per barrier)
# speedup vs baseline: 1.0037x; 1.0037x over previous
; __device__ __forceinline__ unsigned xb_ld(unsigned* p)              { return __hip_atomic_load(p, __ATOMIC_RELAXED, __HIP_MEMORY_SCOPE_AGENT); }
; __device__ __forceinline__ unsigned xb_add(unsigned* p, unsigned v) { return __hip_atomic_fetch_add(p, v, __ATOMIC_RELAXED, __HIP_MEMORY_SCOPE_AGENT); }
; #define XB_SPIN(cond, bar) do { unsigned _sp = 0; while (cond) { __builtin_amdgcn_s_sleep(1); \
;     if ((++_sp & 255u) == 0u) { if (xb_ld(&(bar)[XB_TMO])) break; if (_sp > XB_SPIN_CAP) { atomicAdd(&(bar)[XB_TMO], 1u); break; } } } } while (0)
; __device__ __forceinline__ void xcd_barrier(const XcdBarrier& b) {
;     ...
;         __builtin_amdgcn_s_waitcnt(0);
;         unsigned nloc = b.st[0], nx = b.st[1];
;         if (nloc == 0u) { xcd_barrier_complete(bar, b.x, nloc, nx); b.st[0] = nloc; b.st[1] = nx; }
;         const unsigned old = xb_add(&bar[XB_XSUB(b.x)], 1u);
;         const unsigned gen = old / nloc;
;         if (old + 1u == (gen + 1u) * nloc) {
;             __builtin_amdgcn_fence(__ATOMIC_RELEASE, "agent");
;             asm volatile("s_waitcnt vmcnt(0)" ::: "memory");
;             const unsigned og = xb_add(&bar[XB_TOP], 1u);
;             const unsigned tg = og / nx;
;             if (og + 1u == (tg + 1u) * nx) xb_add(&bar[XB_TOPGEN], 1u);
;             else XB_SPIN(xb_ld(&bar[XB_TOPGEN]) == tg, bar);
;             __builtin_amdgcn_fence(__ATOMIC_ACQUIRE, "agent");
;             xb_add(&bar[XB_XGEN(b.x)], 1u);
;             asm volatile("s_waitcnt vmcnt(0)" ::: "memory");
;         } else {
;             XB_SPIN(xb_ld(&bar[XB_XGEN(b.x)]) == gen, bar);
.LBB0_784:
	v_readlane_b32 s10, v254, 20
	v_readlane_b32 s11, v254, 21
	v_mov_b32_e32 v1, 1
	v_sub_u32_e32 v4, 0, v2
	s_nop 2
	global_atomic_add v3, v153, v1, s[10:11] sc0
	v_cvt_f32_u32_e32 v1, v2
	v_rcp_iflag_f32_e32 v1, v1
	s_nop 0
	v_mul_f32_e32 v1, 0x4f7ffffe, v1
	v_cvt_u32_f32_e32 v1, v1
	v_mul_lo_u32 v4, v4, v1
	v_mul_hi_u32 v4, v1, v4
	v_add_u32_e32 v1, v1, v4
	s_waitcnt vmcnt(0)
	v_mul_hi_u32 v1, v3, v1
	v_mul_lo_u32 v4, v1, v2
	v_sub_u32_e32 v4, v3, v4
	v_add_u32_e32 v5, 1, v1
	v_cmp_ge_u32_e32 vcc, v4, v2
	v_add_u32_e32 v3, 1, v3
	s_nop 0
	v_cndmask_b32_e32 v1, v1, v5, vcc
	v_sub_u32_e32 v5, v4, v2
	v_cndmask_b32_e32 v4, v4, v5, vcc
	v_add_u32_e32 v5, 1, v1
	v_cmp_ge_u32_e32 vcc, v4, v2
	s_nop 1
	v_cndmask_b32_e32 v1, v1, v5, vcc
	v_mul_lo_u32 v4, v2, v1
	v_add_u32_e32 v2, v4, v2
	v_cmp_ne_u32_e32 vcc, v3, v2
	s_and_saveexec_b64 s[10:11], vcc
	s_xor_b64 s[10:11], exec, s[10:11]
	s_cbranch_execz .LBB0_798
	v_readlane_b32 s12, v254, 26
	v_readlane_b32 s13, v254, 27
	s_waitcnt lgkmcnt(0)
	s_nop 3
	global_load_dword v0, v153, s[12:13] sc1
	s_waitcnt vmcnt(0)
	v_cmp_eq_u32_e32 vcc, v0, v1
	s_and_saveexec_b64 s[12:13], vcc
	s_cbranch_execz .LBB0_797
	s_mov_b32 s26, 1
	s_mov_b64 s[14:15], 0
	s_branch .LBB0_788

; __device__ __forceinline__ unsigned xb_ld(unsigned* p)              { return __hip_atomic_load(p, __ATOMIC_RELAXED, __HIP_MEMORY_SCOPE_AGENT); }
; #define XB_SPIN(cond, bar) do { unsigned _sp = 0; while (cond) { __builtin_amdgcn_s_sleep(1); \
;     if ((++_sp & 255u) == 0u) { if (xb_ld(&(bar)[XB_TMO])) break; if (_sp > XB_SPIN_CAP) { atomicAdd(&(bar)[XB_TMO], 1u); break; } } } } while (0)
; __device__ __forceinline__ void xcd_barrier(const XcdBarrier& b) {
;     ...
;             XB_SPIN(xb_ld(&bar[XB_XGEN(b.x)]) == gen, bar);
.LBB0_792:
	v_readlane_b32 s22, v254, 26
	v_readlane_b32 s23, v254, 27
	s_add_i32 s26, s26, 1
	s_mov_b64 s[24:25], -1
	s_nop 2
	global_load_dword v0, v153, s[22:23] sc1
	s_waitcnt vmcnt(0)
	v_cmp_ne_u32_e32 vcc, v0, v1
	s_orn2_b64 s[22:23], vcc, exec
	s_branch .LBB0_787
